# GEMM main loop: 8 of the 16 LDS-DMA loads per 2 K-steps use the scalar-base + 32-bit lane offset form instead of 64-bit VALU address adds
# speedup vs baseline: 1.0065x; 1.0026x over previous
; #define PG8_STAGE(bufoff, gbase, voff) do { _Pragma("unroll") for (int _i = 0; _i < 2; ++_i) \
;         __builtin_amdgcn_global_load_lds((const unsigned*)((const char*)(gbase) + (voff)[_i]), (LAS unsigned*)(lds + (bufoff) + ldsw + _i * 8192), 16, 0, 0); } while (0)
; #define PG8_LDA(dst, b, h) do { _Pragma("unroll") for (int m = 0; m < 4; ++m) _Pragma("unroll") for (int k = 0; k < 2; ++k) dst[m][k] = *(const LAS h16x8*)(lds + PG8_SA(b, h) + aoff + m * 2048 + k * 1024); } while (0)
; #define PG8_LDB(dst, b, h) do { _Pragma("unroll") for (int n = 0; n < 2; ++n) _Pragma("unroll") for (int k = 0; k < 2; ++k) dst[n][k] = *(const LAS h16x8*)(lds + PG8_SB(b, h) + boff + n * 2048 + k * 1024); } while (0)
; #define PG8_MMA(ai, bj, At, Bt) do { __builtin_amdgcn_s_setprio(1); _Pragma("unroll") for (int m = 0; m < 4; ++m) _Pragma("unroll") for (int n = 0; n < 2; ++n) _Pragma("unroll") for (int k = 0; k < 2; ++k) \
;         acc[ai][bj][m][n] = __builtin_amdgcn_mfma_f32_16x16x32_f16(Bt[n][k], At[m][k], acc[ai][bj][m][n], 0, 0, 0); __builtin_amdgcn_s_setprio(0); } while (0)
; #define PG8_WAIT_V(n) asm volatile("s_waitcnt vmcnt(" #n ")" ::: "memory")
; #define PG8_WAIT_L(n) asm volatile("s_waitcnt lgkmcnt(" #n ")" ::: "memory")
; #define PG8_BAR __builtin_amdgcn_s_barrier()
; __device__ __forceinline__ void gemm_phase(LAS unsigned char* lds, const Gemm g, const StaticOrder& S, const Epi& E) {
;     ...
;         for (int t = 0; t < nt; t += 2) {
;             const bool last = (t == nt - 2);
;             const char* a1 = cA + PG8_KOFF(t + 1);
;             const char* a2 = last ? nA : cA + PG8_KOFF(t + 2); const char* b2 = last ? nB : cB + (size_t)(t + 2) * kstep;
;             const char* a3 = a2 + kstep; const char* b3 = b2 + kstep;
;             PG8_LDB(B0, 0, 0); PG8_SCHED; PG8_LDA(At, 0, 0); PG8_STAGE(PG8_SA(1, 1), a1 + hstepA, voffA);
;             PG8_WAIT_L(8); PG8_BAR; PG8_WAIT_L(0); PG8_MMA(0, 0, At, B0); PG8_BAR; PG8_SCHED;
;             PG8_LDB(B1, 0, 1); PG8_STAGE(PG8_SB(0, 0), b2, voffB);
;             PG8_BAR; PG8_WAIT_L(0); PG8_MMA(0, 1, At, B1); PG8_BAR;
;             PG8_LDA(At, 0, 1); PG8_STAGE(PG8_SA(0, 0), a2, voffA);
;             PG8_BAR; PG8_WAIT_L(0); PG8_MMA(1, 0, At, B0); PG8_BAR; PG8_SCHED;
;             PG8_STAGE(PG8_SB(0, 1), b2 + hstepB, voffB);
;             PG8_WAIT_V(6); PG8_BAR; PG8_MMA(1, 1, At, B1); PG8_BAR;
.Lprio_skip:
.LBB0_762:
	s_cmp_gt_u32 s34, 15
	s_cselect_b64 s[36:37], -1, 0
	s_and_b64 s[36:37], s[6:7], s[36:37]
	s_and_b64 s[36:37], s[36:37], exec
	s_cselect_b32 s42, 0xfffff000, 0
	s_cselect_b32 s43, -1, 0
	s_add_i32 s38, s34, 2
	s_cmp_gt_u32 s34, 13
	s_cselect_b64 s[36:37], -1, 0
	s_and_b64 s[36:37], s[6:7], s[36:37]
	s_and_b64 s[36:37], s[36:37], exec
	s_cselect_b32 s36, 0xfffff000, 0
	s_cselect_b32 s35, -1, 0
	s_add_u32 s36, s0, s36
	s_addc_u32 s35, s1, s35
	s_add_u32 s36, s36, 0x80
	s_addc_u32 s35, s35, 0
	s_add_i32 s39, 0, 0x10000
	v_add_u32_e32 v140, s39, v238
	ds_read_b128 v[128:131], v140
	ds_read_b128 v[132:135], v140 offset:1024
	ds_read_b128 v[136:139], v140 offset:2048
	ds_read_b128 v[140:143], v140 offset:3072
	s_cmp_eq_u32 s66, s34
	s_cselect_b32 s34, s4, s36
	s_cselect_b32 s35, s5, s35
	s_cselect_b32 s37, s29, s33
	s_cselect_b32 s36, s28, s27
	s_add_u32 s86, s0, s42
	s_addc_u32 s87, s1, s43
	s_add_i32 m0, s58, 0xc000
	ds_read_b128 v[144:147], v239
	ds_read_b128 v[148:151], v239 offset:1024
	ds_read_b128 v[152:155], v239 offset:2048
	ds_read_b128 v[156:159], v239 offset:3072
	ds_read_b128 v[160:163], v239 offset:4096
	ds_read_b128 v[164:167], v239 offset:5120
	ds_read_b128 v[168:171], v239 offset:6144
	ds_read_b128 v[172:175], v239 offset:7168
	global_load_lds_dwordx4 v212, s[86:87]
	s_add_i32 m0, s58, 0xe000
	s_nop 0
	global_load_lds_dwordx4 v214, s[86:87]
	s_waitcnt lgkmcnt(8)
	s_barrier
	s_waitcnt lgkmcnt(0)
	s_waitcnt lgkmcnt(0)
	v_mfma_f32_16x16x32_f16 v[124:127], v[128:131], v[144:147], v[124:127]
	v_mfma_f32_16x16x32_f16 v[120:123], v[136:139], v[144:147], v[120:123]
	v_mfma_f32_16x16x32_f16 v[108:111], v[128:131], v[152:155], v[108:111]
	v_mfma_f32_16x16x32_f16 v[104:107], v[136:139], v[152:155], v[104:107]
	v_mfma_f32_16x16x32_f16 v[92:95], v[128:131], v[160:163], v[92:95]
	v_mfma_f32_16x16x32_f16 v[88:91], v[136:139], v[160:163], v[88:91]
	v_mfma_f32_16x16x32_f16 v[76:79], v[128:131], v[168:171], v[76:79]
	v_mfma_f32_16x16x32_f16 v[72:75], v[136:139], v[168:171], v[72:75]
	v_mfma_f32_16x16x32_f16 v[124:127], v[132:135], v[148:151], v[124:127]
	v_mfma_f32_16x16x32_f16 v[120:123], v[140:143], v[148:151], v[120:123]
	v_mfma_f32_16x16x32_f16 v[108:111], v[132:135], v[156:159], v[108:111]
	v_mfma_f32_16x16x32_f16 v[104:107], v[140:143], v[156:159], v[104:107]
	v_mfma_f32_16x16x32_f16 v[92:95], v[132:135], v[164:167], v[92:95]
	v_mfma_f32_16x16x32_f16 v[88:91], v[140:143], v[164:167], v[88:91]
	v_mfma_f32_16x16x32_f16 v[76:79], v[132:135], v[172:175], v[76:79]
	v_mfma_f32_16x16x32_f16 v[72:75], v[140:143], v[172:175], v[72:75]
	s_barrier
	s_add_i32 s42, 0, 0x14000
	s_add_i32 s39, s39, s31
	v_add_u32_e32 v188, s42, v238
	s_add_u32 s86, s36, 0x80
	s_addc_u32 s87, s37, 0
	s_mov_b32 m0, s39
	ds_read_b128 v[176:179], v188
	ds_read_b128 v[180:183], v188 offset:1024
	ds_read_b128 v[184:187], v188 offset:2048
	ds_read_b128 v[188:191], v188 offset:3072
	global_load_lds_dwordx4 v206, s[36:37]
	s_add_i32 m0, s39, 0x2000
	s_nop 0
	global_load_lds_dwordx4 v210, s[36:37]
	s_barrier
	s_waitcnt lgkmcnt(0)
	s_waitcnt lgkmcnt(0)
	v_mfma_f32_16x16x32_f16 v[116:119], v[176:179], v[144:147], v[116:119]
	v_mfma_f32_16x16x32_f16 v[112:115], v[184:187], v[144:147], v[112:115]
	v_mfma_f32_16x16x32_f16 v[100:103], v[176:179], v[152:155], v[100:103]
	v_mfma_f32_16x16x32_f16 v[96:99], v[184:187], v[152:155], v[96:99]
	v_mfma_f32_16x16x32_f16 v[84:87], v[176:179], v[160:163], v[84:87]
	v_mfma_f32_16x16x32_f16 v[80:83], v[184:187], v[160:163], v[80:83]
	v_mfma_f32_16x16x32_f16 v[68:71], v[176:179], v[168:171], v[68:71]
	v_mfma_f32_16x16x32_f16 v[64:67], v[184:187], v[168:171], v[64:67]
	v_mfma_f32_16x16x32_f16 v[116:119], v[180:183], v[148:151], v[116:119]
	v_mfma_f32_16x16x32_f16 v[112:115], v[188:191], v[148:151], v[112:115]
	v_mfma_f32_16x16x32_f16 v[100:103], v[180:183], v[156:159], v[100:103]
	v_mfma_f32_16x16x32_f16 v[96:99], v[188:191], v[156:159], v[96:99]
	v_mfma_f32_16x16x32_f16 v[84:87], v[180:183], v[164:167], v[84:87]
	v_mfma_f32_16x16x32_f16 v[80:83], v[188:191], v[164:167], v[80:83]
	v_mfma_f32_16x16x32_f16 v[68:71], v[180:183], v[172:175], v[68:71]
	v_mfma_f32_16x16x32_f16 v[64:67], v[188:191], v[172:175], v[64:67]
	s_mov_b32 m0, s58
	v_lshl_add_u64 v[216:217], s[34:35], 0, v[204:205]
	s_barrier
	ds_read_b128 v[144:147], v239 offset:16384
	ds_read_b128 v[148:151], v239 offset:17408
	ds_read_b128 v[152:155], v239 offset:18432
	ds_read_b128 v[156:159], v239 offset:19456
	ds_read_b128 v[160:163], v239 offset:20480
	ds_read_b128 v[164:167], v239 offset:21504
	ds_read_b128 v[168:171], v239 offset:22528
	ds_read_b128 v[172:175], v239 offset:23552
	global_load_lds_dwordx4 v[216:217], off
	v_lshl_add_u64 v[218:219], s[34:35], 0, v[208:209]
	s_mov_b32 m0, s59
	s_nop 0
	global_load_lds_dwordx4 v[218:219], off
	s_barrier
	s_waitcnt lgkmcnt(0)
	s_waitcnt lgkmcnt(0)
	v_mfma_f32_16x16x32_f16 v[60:63], v[128:131], v[144:147], v[60:63]
	v_mfma_f32_16x16x32_f16 v[56:59], v[136:139], v[144:147], v[56:59]
	v_mfma_f32_16x16x32_f16 v[44:47], v[128:131], v[152:155], v[44:47]
	v_mfma_f32_16x16x32_f16 v[40:43], v[136:139], v[152:155], v[40:43]
	v_mfma_f32_16x16x32_f16 v[28:31], v[128:131], v[160:163], v[28:31]
	v_mfma_f32_16x16x32_f16 v[24:27], v[136:139], v[160:163], v[24:27]
	v_mfma_f32_16x16x32_f16 v[12:15], v[128:131], v[168:171], v[12:15]
	v_mfma_f32_16x16x32_f16 v[8:11], v[136:139], v[168:171], v[8:11]
	v_mfma_f32_16x16x32_f16 v[60:63], v[132:135], v[148:151], v[60:63]
	v_mfma_f32_16x16x32_f16 v[56:59], v[140:143], v[148:151], v[56:59]
	v_mfma_f32_16x16x32_f16 v[44:47], v[132:135], v[156:159], v[44:47]
	v_mfma_f32_16x16x32_f16 v[40:43], v[140:143], v[156:159], v[40:43]
	v_mfma_f32_16x16x32_f16 v[28:31], v[132:135], v[164:167], v[28:31]
	v_mfma_f32_16x16x32_f16 v[24:27], v[140:143], v[164:167], v[24:27]
	v_mfma_f32_16x16x32_f16 v[12:15], v[132:135], v[172:175], v[12:15]
	v_mfma_f32_16x16x32_f16 v[8:11], v[140:143], v[172:175], v[8:11]
	s_barrier
; #define PG8_STAGE(bufoff, gbase, voff) do { _Pragma("unroll") for (int _i = 0; _i < 2; ++_i) \
;         __builtin_amdgcn_global_load_lds((const unsigned*)((const char*)(gbase) + (voff)[_i]), (LAS unsigned*)(lds + (bufoff) + ldsw + _i * 8192), 16, 0, 0); } while (0)
; #define PG8_LDA(dst, b, h) do { _Pragma("unroll") for (int m = 0; m < 4; ++m) _Pragma("unroll") for (int k = 0; k < 2; ++k) dst[m][k] = *(const LAS h16x8*)(lds + PG8_SA(b, h) + aoff + m * 2048 + k * 1024); } while (0)
; #define PG8_LDB(dst, b, h) do { _Pragma("unroll") for (int n = 0; n < 2; ++n) _Pragma("unroll") for (int k = 0; k < 2; ++k) dst[n][k] = *(const LAS h16x8*)(lds + PG8_SB(b, h) + boff + n * 2048 + k * 1024); } while (0)
; #define PG8_MMA(ai, bj, At, Bt) do { __builtin_amdgcn_s_setprio(1); _Pragma("unroll") for (int m = 0; m < 4; ++m) _Pragma("unroll") for (int n = 0; n < 2; ++n) _Pragma("unroll") for (int k = 0; k < 2; ++k) \
;         acc[ai][bj][m][n] = __builtin_amdgcn_mfma_f32_16x16x32_f16(Bt[n][k], At[m][k], acc[ai][bj][m][n], 0, 0, 0); __builtin_amdgcn_s_setprio(0); } while (0)
; #define PG8_WAIT_V(n) asm volatile("s_waitcnt vmcnt(" #n ")" ::: "memory")
; #define PG8_WAIT_L(n) asm volatile("s_waitcnt lgkmcnt(" #n ")" ::: "memory")
; #define PG8_BAR __builtin_amdgcn_s_barrier()
; #define PG8_SCHED __builtin_amdgcn_sched_barrier(0)
; __device__ __forceinline__ void gemm_phase(LAS unsigned char* lds, const Gemm g, const StaticOrder& S, const Epi& E) {
;     ...
;             PG8_WAIT_V(6); PG8_BAR; PG8_MMA(1, 1, At, B1); PG8_BAR;
;             PG8_LDB(B0, 1, 0); PG8_SCHED; PG8_LDA(At, 1, 0); PG8_STAGE(PG8_SA(0, 1), a2 + hstepA, voffA);
;             PG8_WAIT_L(8); PG8_BAR; PG8_WAIT_L(0); PG8_MMA(0, 0, At, B0); PG8_BAR; PG8_SCHED;
;             PG8_LDB(B1, 1, 1); PG8_STAGE(PG8_SB(1, 0), b3, voffB);
;             PG8_BAR; PG8_WAIT_L(0); PG8_MMA(0, 1, At, B1); PG8_BAR;
;             PG8_LDA(At, 1, 1); PG8_STAGE(PG8_SA(1, 0), a3, voffA);
	s_add_u32 s36, s36, s18
	s_addc_u32 s37, s37, s19
	s_add_i32 s39, s42, s31
	v_lshl_add_u64 v[220:221], s[36:37], 0, v[206:207]
	s_mov_b32 m0, s39
	v_lshl_add_u64 v[222:223], s[36:37], 0, v[210:211]
	global_load_lds_dwordx4 v[220:221], off
	s_add_i32 m0, s39, 0x2000
	s_nop 0
	global_load_lds_dwordx4 v[222:223], off
	s_waitcnt vmcnt(6)
	s_barrier
	v_mfma_f32_16x16x32_f16 v[52:55], v[176:179], v[144:147], v[52:55]
	v_mfma_f32_16x16x32_f16 v[48:51], v[184:187], v[144:147], v[48:51]
	v_mfma_f32_16x16x32_f16 v[36:39], v[176:179], v[152:155], v[36:39]
	v_mfma_f32_16x16x32_f16 v[32:35], v[184:187], v[152:155], v[32:35]
	v_mfma_f32_16x16x32_f16 v[20:23], v[176:179], v[160:163], v[20:23]
	v_mfma_f32_16x16x32_f16 v[16:19], v[184:187], v[160:163], v[16:19]
	v_mfma_f32_16x16x32_f16 v[4:7], v[176:179], v[168:171], v[4:7]
	v_mfma_f32_16x16x32_f16 v[0:3], v[184:187], v[168:171], v[0:3]
	v_mfma_f32_16x16x32_f16 v[52:55], v[180:183], v[148:151], v[52:55]
	v_mfma_f32_16x16x32_f16 v[48:51], v[188:191], v[148:151], v[48:51]
	v_mfma_f32_16x16x32_f16 v[36:39], v[180:183], v[156:159], v[36:39]
	v_mfma_f32_16x16x32_f16 v[32:35], v[188:191], v[156:159], v[32:35]
	v_mfma_f32_16x16x32_f16 v[20:23], v[180:183], v[164:167], v[20:23]
	v_mfma_f32_16x16x32_f16 v[16:19], v[188:191], v[164:167], v[16:19]
	v_mfma_f32_16x16x32_f16 v[4:7], v[180:183], v[172:175], v[4:7]
	v_mfma_f32_16x16x32_f16 v[0:3], v[188:191], v[172:175], v[0:3]
	s_add_i32 s36, 0, 0x18000
	v_add_u32_e32 v140, s36, v238
	s_barrier
	ds_read_b128 v[128:131], v140
	ds_read_b128 v[132:135], v140 offset:1024
	ds_read_b128 v[136:139], v140 offset:2048
	ds_read_b128 v[140:143], v140 offset:3072
	s_add_u32 s34, s34, s16
	s_addc_u32 s35, s35, s17
	s_mov_b32 m0, s60
	ds_read_b128 v[144:147], v239 offset:32768
	ds_read_b128 v[148:151], v239 offset:33792
	ds_read_b128 v[152:155], v239 offset:34816
	ds_read_b128 v[156:159], v239 offset:35840
	ds_read_b128 v[160:163], v239 offset:36864
	ds_read_b128 v[164:167], v239 offset:37888
	ds_read_b128 v[168:171], v239 offset:38912
	ds_read_b128 v[172:175], v239 offset:39936
	global_load_lds_dwordx4 v204, s[34:35]
	s_mov_b32 m0, s61
	s_nop 0
	global_load_lds_dwordx4 v208, s[34:35]
	s_waitcnt lgkmcnt(8)
	s_barrier
	s_waitcnt lgkmcnt(0)
	s_waitcnt lgkmcnt(0)
	v_mfma_f32_16x16x32_f16 v[124:127], v[128:131], v[144:147], v[124:127]
	v_mfma_f32_16x16x32_f16 v[120:123], v[136:139], v[144:147], v[120:123]
	v_mfma_f32_16x16x32_f16 v[108:111], v[128:131], v[152:155], v[108:111]
	v_mfma_f32_16x16x32_f16 v[104:107], v[136:139], v[152:155], v[104:107]
	v_mfma_f32_16x16x32_f16 v[92:95], v[128:131], v[160:163], v[92:95]
	v_mfma_f32_16x16x32_f16 v[88:91], v[136:139], v[160:163], v[88:91]
	v_mfma_f32_16x16x32_f16 v[76:79], v[128:131], v[168:171], v[76:79]
	v_mfma_f32_16x16x32_f16 v[72:75], v[136:139], v[168:171], v[72:75]
	v_mfma_f32_16x16x32_f16 v[124:127], v[132:135], v[148:151], v[124:127]
	v_mfma_f32_16x16x32_f16 v[120:123], v[140:143], v[148:151], v[120:123]
	v_mfma_f32_16x16x32_f16 v[108:111], v[132:135], v[156:159], v[108:111]
	v_mfma_f32_16x16x32_f16 v[104:107], v[140:143], v[156:159], v[104:107]
	v_mfma_f32_16x16x32_f16 v[92:95], v[132:135], v[164:167], v[92:95]
	v_mfma_f32_16x16x32_f16 v[88:91], v[140:143], v[164:167], v[88:91]
	v_mfma_f32_16x16x32_f16 v[76:79], v[132:135], v[172:175], v[76:79]
	v_mfma_f32_16x16x32_f16 v[72:75], v[140:143], v[172:175], v[72:75]
	s_barrier
	s_add_i32 s34, 0, 0x1c000
	s_add_i32 s35, s36, s31
	v_add_u32_e32 v188, s34, v238
	s_mov_b32 m0, s35
	ds_read_b128 v[176:179], v188
	ds_read_b128 v[180:183], v188 offset:1024
	ds_read_b128 v[184:187], v188 offset:2048
	ds_read_b128 v[188:191], v188 offset:3072
	global_load_lds_dwordx4 v206, s[86:87]
	s_add_i32 m0, s35, 0x2000
	s_nop 0
	global_load_lds_dwordx4 v210, s[86:87]
	s_barrier
; #define PG8_STAGE(bufoff, gbase, voff) do { _Pragma("unroll") for (int _i = 0; _i < 2; ++_i) \
;         __builtin_amdgcn_global_load_lds((const unsigned*)((const char*)(gbase) + (voff)[_i]), (LAS unsigned*)(lds + (bufoff) + ldsw + _i * 8192), 16, 0, 0); } while (0)
; #define PG8_LDA(dst, b, h) do { _Pragma("unroll") for (int m = 0; m < 4; ++m) _Pragma("unroll") for (int k = 0; k < 2; ++k) dst[m][k] = *(const LAS h16x8*)(lds + PG8_SA(b, h) + aoff + m * 2048 + k * 1024); } while (0)
; #define PG8_MMA(ai, bj, At, Bt) do { __builtin_amdgcn_s_setprio(1); _Pragma("unroll") for (int m = 0; m < 4; ++m) _Pragma("unroll") for (int n = 0; n < 2; ++n) _Pragma("unroll") for (int k = 0; k < 2; ++k) \
;         acc[ai][bj][m][n] = __builtin_amdgcn_mfma_f32_16x16x32_f16(Bt[n][k], At[m][k], acc[ai][bj][m][n], 0, 0, 0); __builtin_amdgcn_s_setprio(0); } while (0)
; #define PG8_WAIT_V(n) asm volatile("s_waitcnt vmcnt(" #n ")" ::: "memory")
; #define PG8_WAIT_L(n) asm volatile("s_waitcnt lgkmcnt(" #n ")" ::: "memory")
; #define PG8_BAR __builtin_amdgcn_s_barrier()
; #define PG8_SCHED __builtin_amdgcn_sched_barrier(0)
; __device__ __forceinline__ void gemm_phase(LAS unsigned char* lds, const Gemm g, const StaticOrder& S, const Epi& E) {
;     ...
;             PG8_LDA(At, 1, 1); PG8_STAGE(PG8_SA(1, 0), a3, voffA);
;             PG8_BAR; PG8_WAIT_L(0); PG8_MMA(1, 0, At, B0); PG8_BAR; PG8_SCHED;
;             PG8_STAGE(PG8_SB(1, 1), b3 + hstepB, voffB);
;             PG8_WAIT_V(6); PG8_BAR; PG8_MMA(1, 1, At, B1); PG8_BAR;
	s_waitcnt lgkmcnt(0)
	s_waitcnt lgkmcnt(0)
	v_mfma_f32_16x16x32_f16 v[116:119], v[176:179], v[144:147], v[116:119]
	v_mfma_f32_16x16x32_f16 v[112:115], v[184:187], v[144:147], v[112:115]
	v_mfma_f32_16x16x32_f16 v[100:103], v[176:179], v[152:155], v[100:103]
	v_mfma_f32_16x16x32_f16 v[96:99], v[184:187], v[152:155], v[96:99]
	v_mfma_f32_16x16x32_f16 v[84:87], v[176:179], v[160:163], v[84:87]
	v_mfma_f32_16x16x32_f16 v[80:83], v[184:187], v[160:163], v[80:83]
	v_mfma_f32_16x16x32_f16 v[68:71], v[176:179], v[168:171], v[68:71]
	v_mfma_f32_16x16x32_f16 v[64:67], v[184:187], v[168:171], v[64:67]
	v_mfma_f32_16x16x32_f16 v[116:119], v[180:183], v[148:151], v[116:119]
	v_mfma_f32_16x16x32_f16 v[112:115], v[188:191], v[148:151], v[112:115]
	v_mfma_f32_16x16x32_f16 v[100:103], v[180:183], v[156:159], v[100:103]
	v_mfma_f32_16x16x32_f16 v[96:99], v[188:191], v[156:159], v[96:99]
	v_mfma_f32_16x16x32_f16 v[84:87], v[180:183], v[164:167], v[84:87]
	v_mfma_f32_16x16x32_f16 v[80:83], v[188:191], v[164:167], v[80:83]
	v_mfma_f32_16x16x32_f16 v[68:71], v[180:183], v[172:175], v[68:71]
	v_mfma_f32_16x16x32_f16 v[64:67], v[188:191], v[172:175], v[64:67]
	s_mov_b32 m0, s62
	v_lshl_add_u64 v[192:193], v[216:217], 0, s[80:81]
	s_barrier
	ds_read_b128 v[144:147], v239 offset:49152
	ds_read_b128 v[148:151], v239 offset:50176
	ds_read_b128 v[152:155], v239 offset:51200
	ds_read_b128 v[156:159], v239 offset:52224
	ds_read_b128 v[160:163], v239 offset:53248
	ds_read_b128 v[164:167], v239 offset:54272
	ds_read_b128 v[168:171], v239 offset:55296
	ds_read_b128 v[172:175], v239 offset:56320
	global_load_lds_dwordx4 v[192:193], off
	v_lshl_add_u64 v[192:193], v[218:219], 0, s[80:81]
	s_mov_b32 m0, s63
	s_nop 0
	global_load_lds_dwordx4 v[192:193], off
	s_barrier
	s_waitcnt lgkmcnt(0)
	s_waitcnt lgkmcnt(0)
	v_mfma_f32_16x16x32_f16 v[60:63], v[128:131], v[144:147], v[60:63]
	v_mfma_f32_16x16x32_f16 v[56:59], v[136:139], v[144:147], v[56:59]
	v_mfma_f32_16x16x32_f16 v[44:47], v[128:131], v[152:155], v[44:47]
	v_mfma_f32_16x16x32_f16 v[40:43], v[136:139], v[152:155], v[40:43]
	v_mfma_f32_16x16x32_f16 v[28:31], v[128:131], v[160:163], v[28:31]
	v_mfma_f32_16x16x32_f16 v[24:27], v[136:139], v[160:163], v[24:27]
	v_mfma_f32_16x16x32_f16 v[12:15], v[128:131], v[168:171], v[12:15]
	v_mfma_f32_16x16x32_f16 v[8:11], v[136:139], v[168:171], v[8:11]
	v_mfma_f32_16x16x32_f16 v[60:63], v[132:135], v[148:151], v[60:63]
	v_mfma_f32_16x16x32_f16 v[56:59], v[140:143], v[148:151], v[56:59]
	v_mfma_f32_16x16x32_f16 v[44:47], v[132:135], v[156:159], v[44:47]
	v_mfma_f32_16x16x32_f16 v[40:43], v[140:143], v[156:159], v[40:43]
	v_mfma_f32_16x16x32_f16 v[28:31], v[132:135], v[164:167], v[28:31]
	v_mfma_f32_16x16x32_f16 v[24:27], v[140:143], v[164:167], v[24:27]
	v_mfma_f32_16x16x32_f16 v[12:15], v[132:135], v[172:175], v[12:15]
	v_mfma_f32_16x16x32_f16 v[8:11], v[140:143], v[172:175], v[8:11]
	s_barrier
	s_add_i32 s34, s34, s31
	v_lshl_add_u64 v[128:129], v[220:221], 0, s[80:81]
	s_mov_b32 m0, s34
	s_nop 0
	global_load_lds_dwordx4 v[128:129], off
	v_lshl_add_u64 v[128:129], v[222:223], 0, s[80:81]
	s_add_i32 m0, s34, 0x2000
	s_nop 0
	global_load_lds_dwordx4 v[128:129], off
	s_waitcnt vmcnt(6)
	s_barrier
	v_mfma_f32_16x16x32_f16 v[52:55], v[176:179], v[144:147], v[52:55]
	v_mfma_f32_16x16x32_f16 v[48:51], v[184:187], v[144:147], v[48:51]
	v_mfma_f32_16x16x32_f16 v[36:39], v[176:179], v[152:155], v[36:39]
	v_mfma_f32_16x16x32_f16 v[32:35], v[184:187], v[152:155], v[32:35]
	v_mfma_f32_16x16x32_f16 v[20:23], v[176:179], v[160:163], v[20:23]
	v_mfma_f32_16x16x32_f16 v[16:19], v[184:187], v[160:163], v[16:19]
	v_mfma_f32_16x16x32_f16 v[4:7], v[176:179], v[168:171], v[4:7]
	v_mfma_f32_16x16x32_f16 v[0:3], v[184:187], v[168:171], v[0:3]
	v_mfma_f32_16x16x32_f16 v[52:55], v[180:183], v[148:151], v[52:55]
	v_mfma_f32_16x16x32_f16 v[48:51], v[188:191], v[148:151], v[48:51]
	v_mfma_f32_16x16x32_f16 v[36:39], v[180:183], v[156:159], v[36:39]
	v_mfma_f32_16x16x32_f16 v[32:35], v[188:191], v[156:159], v[32:35]
	v_mfma_f32_16x16x32_f16 v[20:23], v[180:183], v[164:167], v[20:23]
	v_mfma_f32_16x16x32_f16 v[16:19], v[188:191], v[164:167], v[16:19]
	v_mfma_f32_16x16x32_f16 v[4:7], v[180:183], v[172:175], v[4:7]
	v_mfma_f32_16x16x32_f16 v[0:3], v[188:191], v[172:175], v[0:3]
	s_add_u32 s0, s0, 0x100
	s_addc_u32 s1, s1, 0
	s_add_u32 s27, s27, 0x100
	s_addc_u32 s33, s33, 0
	s_cmp_ge_u32 s38, s64
	s_mov_b32 s34, s38
	s_barrier
	s_cbranch_scc0 .LBB0_762
	s_setprio 0
	s_lshl_b32 s0, s84, 8
	s_or_b32 s27, s0, s65
	v_lshl_add_u32 v240, s30, 8, v200
	v_or_b32_e32 v216, s27, v202
	s_cmp_eq_u32 s93, 3
	s_cbranch_scc1 .Lst16_fast
	s_cmp_eq_u32 s93, 1
	s_cbranch_scc0 .Llora_no
	s_lshr_b32 s0, s84, 2
	s_cmp_lt_u32 s0, 2
	s_cbranch_scc1 .Llora_fast
